# P0 rmsnorm loop pipelined (next row in flight, DPP reduce) on top of pipelined P5b and P7b
# speedup vs baseline: 1.0118x; 1.0008x over previous
; __device__ __forceinline__ unsigned pk2(float lo, float hi) { return pg8::cvt_pk_bf16(lo, hi); }
; #define INP(i) ((const float*)(const GAS float*)KARG(8 * (i)))
; #define X_IN INP(0)
; __global__ void __launch_bounds__(512, 2) fwd(Params P) {
;     ...
;         const f32x4* gr = (const f32x4*)INP(3) + lane;
;         for (int m = gw; m < T_TOK; m += NGW) {
;             const f32x4* xr = (const f32x4*)(X_IN + (size_t)m * DM) + lane; f32x4 v[8]; float s = 0.f;
; #pragma unroll
;             for (int j = 0; j < 8; ++j) { v[j] = __builtin_nontemporal_load(&xr[64 * j]); s += (v[j].x * v[j].x + v[j].y * v[j].y) + (v[j].z * v[j].z + v[j].w * v[j].w); }
;             const float rs = __builtin_amdgcn_rsqf(wave_sum(s) * (1.f / DM) + EPS);
;             u32x2* o = (u32x2*)(XN + (size_t)m * DM) + lane;
; #pragma unroll
;             for (int j = 0; j < 8; ++j) { const f32x4 g = gr[64 * j]; u32x2 w; w.x = pk2(v[j].x * rs * g.x, v[j].y * rs * g.y); w.y = pk2(v[j].z * rs * g.z, v[j].w * rs * g.w); o[64 * j] = w; }
;         }
.LBB0_151:
	s_cmp_lt_i32 s80, 0x8000
	s_cselect_b64 s[6:7], -1, 0
	s_mov_b64 s[4:5], s[0:1]
	v_mov_b32_e32 v167, 0
	v_writelane_b32 v246, s6, 4
	s_cmpk_gt_i32 s80, 0x7fff
	v_lshlrev_b32_e32 v166, 4, v179
	v_mbcnt_lo_u32_b32 v180, -1, 0
	v_writelane_b32 v246, s7, 5
	s_cbranch_scc1 .LBB0_154
	s_load_dwordx2 s[8:9], s[0:1], 0x18
	s_load_dwordx2 s[4:5], s[0:1], 0x0
	s_load_dwordx2 s[6:7], s[0:1], 0xa8
	v_lshlrev_b32_e32 v106, 3, v179
	v_mov_b32_e32 v101, 0x358637bd
	s_mov_b32 s12, s80
	s_waitcnt lgkmcnt(0)
	s_add_u32 s10, s8, 0x1000
	s_addc_u32 s11, s9, 0
	s_add_u32 s4, s4, 0x1000
	s_addc_u32 s5, s5, 0
	s_add_u32 s6, s6, 0x8000000
	s_addc_u32 s7, s7, 0
	global_load_dwordx4 v[0:3], v166, s[8:9] offset:0
	global_load_dwordx4 v[4:7], v166, s[8:9] offset:1024
	global_load_dwordx4 v[8:11], v166, s[8:9] offset:2048
	global_load_dwordx4 v[12:15], v166, s[8:9] offset:3072
	global_load_dwordx4 v[16:19], v166, s[10:11] offset:0
	global_load_dwordx4 v[20:23], v166, s[10:11] offset:1024
	global_load_dwordx4 v[24:27], v166, s[10:11] offset:2048
	global_load_dwordx4 v[28:31], v166, s[10:11] offset:3072
	s_lshl_b32 s13, s12, 13
	s_add_u32 s8, s4, s13
	s_addc_u32 s9, s5, 0
	global_load_dwordx4 v[32:35], v166, s[8:9] offset:-4096 nt
	global_load_dwordx4 v[36:39], v166, s[8:9] offset:-3072 nt
	global_load_dwordx4 v[40:43], v166, s[8:9] offset:-2048 nt
	global_load_dwordx4 v[44:47], v166, s[8:9] offset:-1024 nt
	global_load_dwordx4 v[48:51], v166, s[8:9] offset:0 nt
	global_load_dwordx4 v[52:55], v166, s[8:9] offset:1024 nt
	global_load_dwordx4 v[56:59], v166, s[8:9] offset:2048 nt
	global_load_dwordx4 v[60:63], v166, s[8:9] offset:3072 nt
	s_lshl_b32 s13, s12, 12
	s_add_u32 s10, s6, s13
	s_addc_u32 s11, s7, 0
	s_add_i32 s13, s12, s82
	s_cmpk_gt_i32 s13, 0x7fff
	s_cselect_b32 s13, s12, s13
	s_lshl_b32 s13, s13, 13
	s_add_u32 s8, s4, s13
	s_addc_u32 s9, s5, 0
	global_load_dwordx4 v[64:67], v166, s[8:9] offset:-4096 nt
	global_load_dwordx4 v[68:71], v166, s[8:9] offset:-3072 nt
	global_load_dwordx4 v[72:75], v166, s[8:9] offset:-2048 nt
	global_load_dwordx4 v[76:79], v166, s[8:9] offset:-1024 nt
	global_load_dwordx4 v[80:83], v166, s[8:9] offset:0 nt
	global_load_dwordx4 v[84:87], v166, s[8:9] offset:1024 nt
	global_load_dwordx4 v[88:91], v166, s[8:9] offset:2048 nt
	global_load_dwordx4 v[92:95], v166, s[8:9] offset:3072 nt
	s_waitcnt vmcnt(15)
	v_mul_f32_e32 v102, v32, v32
	v_mul_f32_e32 v103, v33, v33
	v_mul_f32_e32 v104, v34, v34
	v_mul_f32_e32 v105, v35, v35
	s_waitcnt vmcnt(14)
	v_fma_f32 v102, v36, v36, v102
	v_fma_f32 v103, v37, v37, v103
	v_fma_f32 v104, v38, v38, v104
	v_fma_f32 v105, v39, v39, v105
	s_waitcnt vmcnt(13)
	v_fma_f32 v102, v40, v40, v102
	v_fma_f32 v103, v41, v41, v103
	v_fma_f32 v104, v42, v42, v104
	v_fma_f32 v105, v43, v43, v105
	s_waitcnt vmcnt(12)
	v_fma_f32 v102, v44, v44, v102
	v_fma_f32 v103, v45, v45, v103
	v_fma_f32 v104, v46, v46, v104
	v_fma_f32 v105, v47, v47, v105
	s_waitcnt vmcnt(11)
	v_fma_f32 v102, v48, v48, v102
	v_fma_f32 v103, v49, v49, v103
	v_fma_f32 v104, v50, v50, v104
	v_fma_f32 v105, v51, v51, v105
	s_waitcnt vmcnt(10)
	v_fma_f32 v102, v52, v52, v102
	v_fma_f32 v103, v53, v53, v103
	v_fma_f32 v104, v54, v54, v104
	v_fma_f32 v105, v55, v55, v105
	s_waitcnt vmcnt(9)
	v_fma_f32 v102, v56, v56, v102
	v_fma_f32 v103, v57, v57, v103
	v_fma_f32 v104, v58, v58, v104
	v_fma_f32 v105, v59, v59, v105
	s_waitcnt vmcnt(8)
	v_fma_f32 v102, v60, v60, v102
	v_fma_f32 v103, v61, v61, v103
	v_fma_f32 v104, v62, v62, v104
	v_fma_f32 v105, v63, v63, v105
	v_add_f32_e32 v102, v102, v103
	v_add_f32_e32 v104, v104, v105
	v_add_f32_e32 v102, v102, v104
	s_nop 1
	v_add_f32_dpp v102, v102, v102 quad_perm:[1,0,3,2] row_mask:0xf bank_mask:0xf
	s_nop 1
	v_add_f32_dpp v102, v102, v102 quad_perm:[2,3,0,1] row_mask:0xf bank_mask:0xf
	s_nop 1
	v_add_f32_dpp v102, v102, v102 row_half_mirror row_mask:0xf bank_mask:0xf
	s_nop 1
	v_add_f32_dpp v102, v102, v102 row_mirror row_mask:0xf bank_mask:0xf
	s_nop 1
	v_readlane_b32 s8, v102, 0
	v_readlane_b32 s9, v102, 16
	v_readlane_b32 vcc_lo, v102, 32
	v_readlane_b32 vcc_hi, v102, 48
	v_mov_b32_e32 v100, s8
	v_add_f32_e32 v100, s9, v100
	v_add_f32_e32 v100, vcc_lo, v100
	v_add_f32_e32 v100, vcc_hi, v100
	v_fmamk_f32 v100, v100, 0x3a000000, v101
	v_rsq_f32_e32 v100, v100
	s_nop 0
	v_mul_f32_e32 v96, v100, v32
	v_mul_f32_e32 v97, v100, v33
	v_mul_f32_e32 v98, v100, v34
	v_mul_f32_e32 v99, v100, v35
	v_mul_f32_e32 v96, v96, v0
	v_mul_f32_e32 v97, v97, v1
	v_mul_f32_e32 v98, v98, v2
	v_mul_f32_e32 v99, v99, v3
	v_cvt_pk_bf16_f32 v32, v96, v97
	v_cvt_pk_bf16_f32 v33, v98, v99
	global_store_dwordx2 v106, v[32:33], s[10:11] offset:0
	v_mul_f32_e32 v96, v100, v36
	v_mul_f32_e32 v97, v100, v37
	v_mul_f32_e32 v98, v100, v38
	v_mul_f32_e32 v99, v100, v39
	v_mul_f32_e32 v96, v96, v4
	v_mul_f32_e32 v97, v97, v5
	v_mul_f32_e32 v98, v98, v6
	v_mul_f32_e32 v99, v99, v7
	v_cvt_pk_bf16_f32 v36, v96, v97
	v_cvt_pk_bf16_f32 v37, v98, v99
	global_store_dwordx2 v106, v[36:37], s[10:11] offset:512
	v_mul_f32_e32 v96, v100, v40
	v_mul_f32_e32 v97, v100, v41
	v_mul_f32_e32 v98, v100, v42
	v_mul_f32_e32 v99, v100, v43
	v_mul_f32_e32 v96, v96, v8
	v_mul_f32_e32 v97, v97, v9
	v_mul_f32_e32 v98, v98, v10
	v_mul_f32_e32 v99, v99, v11
	v_cvt_pk_bf16_f32 v40, v96, v97
	v_cvt_pk_bf16_f32 v41, v98, v99
	global_store_dwordx2 v106, v[40:41], s[10:11] offset:1024
	v_mul_f32_e32 v96, v100, v44
	v_mul_f32_e32 v97, v100, v45
	v_mul_f32_e32 v98, v100, v46
	v_mul_f32_e32 v99, v100, v47
	v_mul_f32_e32 v96, v96, v12
	v_mul_f32_e32 v97, v97, v13
	v_mul_f32_e32 v98, v98, v14
	v_mul_f32_e32 v99, v99, v15
	v_cvt_pk_bf16_f32 v44, v96, v97
; __device__ __forceinline__ unsigned pk2(float lo, float hi) { return pg8::cvt_pk_bf16(lo, hi); }
; #define X_IN INP(0)
; __global__ void __launch_bounds__(512, 2) fwd(Params P) {
;     ...
;         for (int m = gw; m < T_TOK; m += NGW) {
;             const f32x4* xr = (const f32x4*)(X_IN + (size_t)m * DM) + lane; f32x4 v[8]; float s = 0.f;
; #pragma unroll
;             for (int j = 0; j < 8; ++j) { v[j] = __builtin_nontemporal_load(&xr[64 * j]); s += (v[j].x * v[j].x + v[j].y * v[j].y) + (v[j].z * v[j].z + v[j].w * v[j].w); }
;             const float rs = __builtin_amdgcn_rsqf(wave_sum(s) * (1.f / DM) + EPS);
;             u32x2* o = (u32x2*)(XN + (size_t)m * DM) + lane;
; #pragma unroll
;             for (int j = 0; j < 8; ++j) { const f32x4 g = gr[64 * j]; u32x2 w; w.x = pk2(v[j].x * rs * g.x, v[j].y * rs * g.y); w.y = pk2(v[j].z * rs * g.z, v[j].w * rs * g.w); o[64 * j] = w; }
;         }
	v_cvt_pk_bf16_f32 v45, v98, v99
	global_store_dwordx2 v106, v[44:45], s[10:11] offset:1536
	v_mul_f32_e32 v96, v100, v48
	v_mul_f32_e32 v97, v100, v49
	v_mul_f32_e32 v98, v100, v50
	v_mul_f32_e32 v99, v100, v51
	v_mul_f32_e32 v96, v96, v16
	v_mul_f32_e32 v97, v97, v17
	v_mul_f32_e32 v98, v98, v18
	v_mul_f32_e32 v99, v99, v19
	v_cvt_pk_bf16_f32 v48, v96, v97
	v_cvt_pk_bf16_f32 v49, v98, v99
	global_store_dwordx2 v106, v[48:49], s[10:11] offset:2048
	v_mul_f32_e32 v96, v100, v52
	v_mul_f32_e32 v97, v100, v53
	v_mul_f32_e32 v98, v100, v54
	v_mul_f32_e32 v99, v100, v55
	v_mul_f32_e32 v96, v96, v20
	v_mul_f32_e32 v97, v97, v21
	v_mul_f32_e32 v98, v98, v22
	v_mul_f32_e32 v99, v99, v23
	v_cvt_pk_bf16_f32 v52, v96, v97
	v_cvt_pk_bf16_f32 v53, v98, v99
	global_store_dwordx2 v106, v[52:53], s[10:11] offset:2560
	v_mul_f32_e32 v96, v100, v56
	v_mul_f32_e32 v97, v100, v57
	v_mul_f32_e32 v98, v100, v58
	v_mul_f32_e32 v99, v100, v59
	v_mul_f32_e32 v96, v96, v24
	v_mul_f32_e32 v97, v97, v25
	v_mul_f32_e32 v98, v98, v26
	v_mul_f32_e32 v99, v99, v27
	v_cvt_pk_bf16_f32 v56, v96, v97
	v_cvt_pk_bf16_f32 v57, v98, v99
	global_store_dwordx2 v106, v[56:57], s[10:11] offset:3072
	v_mul_f32_e32 v96, v100, v60
	v_mul_f32_e32 v97, v100, v61
	v_mul_f32_e32 v98, v100, v62
	v_mul_f32_e32 v99, v100, v63
	v_mul_f32_e32 v96, v96, v28
	v_mul_f32_e32 v97, v97, v29
	v_mul_f32_e32 v98, v98, v30
	v_mul_f32_e32 v99, v99, v31
	v_cvt_pk_bf16_f32 v60, v96, v97
	v_cvt_pk_bf16_f32 v61, v98, v99
	global_store_dwordx2 v106, v[60:61], s[10:11] offset:3584
	s_add_i32 s12, s12, s82
	s_cmpk_gt_i32 s12, 0x7fff
	s_cbranch_scc1 .Lp0n_done
.Lp0n_loop:
	s_lshl_b32 s13, s12, 12
	s_add_u32 s10, s6, s13
	s_addc_u32 s11, s7, 0
	s_add_i32 s13, s12, s82
	s_cmpk_gt_i32 s13, 0x7fff
	s_cselect_b32 s13, s12, s13
	s_lshl_b32 s13, s13, 13
	s_add_u32 s8, s4, s13
	s_addc_u32 s9, s5, 0
	global_load_dwordx4 v[32:35], v166, s[8:9] offset:-4096 nt
	global_load_dwordx4 v[36:39], v166, s[8:9] offset:-3072 nt
	global_load_dwordx4 v[40:43], v166, s[8:9] offset:-2048 nt
	global_load_dwordx4 v[44:47], v166, s[8:9] offset:-1024 nt
	global_load_dwordx4 v[48:51], v166, s[8:9] offset:0 nt
	global_load_dwordx4 v[52:55], v166, s[8:9] offset:1024 nt
	global_load_dwordx4 v[56:59], v166, s[8:9] offset:2048 nt
	global_load_dwordx4 v[60:63], v166, s[8:9] offset:3072 nt
	s_waitcnt vmcnt(23)
	v_mul_f32_e32 v102, v64, v64
	v_mul_f32_e32 v103, v65, v65
	v_mul_f32_e32 v104, v66, v66
	v_mul_f32_e32 v105, v67, v67
	s_waitcnt vmcnt(22)
	v_fma_f32 v102, v68, v68, v102
	v_fma_f32 v103, v69, v69, v103
	v_fma_f32 v104, v70, v70, v104
	v_fma_f32 v105, v71, v71, v105
	s_waitcnt vmcnt(21)
	v_fma_f32 v102, v72, v72, v102
	v_fma_f32 v103, v73, v73, v103
	v_fma_f32 v104, v74, v74, v104
	v_fma_f32 v105, v75, v75, v105
	s_waitcnt vmcnt(20)
	v_fma_f32 v102, v76, v76, v102
	v_fma_f32 v103, v77, v77, v103
	v_fma_f32 v104, v78, v78, v104
	v_fma_f32 v105, v79, v79, v105
	s_waitcnt vmcnt(19)
	v_fma_f32 v102, v80, v80, v102
	v_fma_f32 v103, v81, v81, v103
	v_fma_f32 v104, v82, v82, v104
	v_fma_f32 v105, v83, v83, v105
	s_waitcnt vmcnt(18)
	v_fma_f32 v102, v84, v84, v102
	v_fma_f32 v103, v85, v85, v103
	v_fma_f32 v104, v86, v86, v104
	v_fma_f32 v105, v87, v87, v105
	s_waitcnt vmcnt(17)
	v_fma_f32 v102, v88, v88, v102
	v_fma_f32 v103, v89, v89, v103
	v_fma_f32 v104, v90, v90, v104
	v_fma_f32 v105, v91, v91, v105
	s_waitcnt vmcnt(16)
	v_fma_f32 v102, v92, v92, v102
	v_fma_f32 v103, v93, v93, v103
	v_fma_f32 v104, v94, v94, v104
	v_fma_f32 v105, v95, v95, v105
	v_add_f32_e32 v102, v102, v103
	v_add_f32_e32 v104, v104, v105
	v_add_f32_e32 v102, v102, v104
	s_nop 1
	v_add_f32_dpp v102, v102, v102 quad_perm:[1,0,3,2] row_mask:0xf bank_mask:0xf
	s_nop 1
	v_add_f32_dpp v102, v102, v102 quad_perm:[2,3,0,1] row_mask:0xf bank_mask:0xf
	s_nop 1
	v_add_f32_dpp v102, v102, v102 row_half_mirror row_mask:0xf bank_mask:0xf
	s_nop 1
	v_add_f32_dpp v102, v102, v102 row_mirror row_mask:0xf bank_mask:0xf
	s_nop 1
	v_readlane_b32 s8, v102, 0
	v_readlane_b32 s9, v102, 16
	v_readlane_b32 vcc_lo, v102, 32
	v_readlane_b32 vcc_hi, v102, 48
	v_mov_b32_e32 v100, s8
	v_add_f32_e32 v100, s9, v100
	v_add_f32_e32 v100, vcc_lo, v100
	v_add_f32_e32 v100, vcc_hi, v100
	v_fmamk_f32 v100, v100, 0x3a000000, v101
	v_rsq_f32_e32 v100, v100
	s_nop 0
	v_mul_f32_e32 v96, v100, v64
	v_mul_f32_e32 v97, v100, v65
	v_mul_f32_e32 v98, v100, v66
	v_mul_f32_e32 v99, v100, v67
	v_mul_f32_e32 v96, v96, v0
	v_mul_f32_e32 v97, v97, v1
	v_mul_f32_e32 v98, v98, v2
	v_mul_f32_e32 v99, v99, v3
	v_cvt_pk_bf16_f32 v64, v96, v97
	v_cvt_pk_bf16_f32 v65, v98, v99
	global_store_dwordx2 v106, v[64:65], s[10:11] offset:0
	v_mul_f32_e32 v96, v100, v68
	v_mul_f32_e32 v97, v100, v69
	v_mul_f32_e32 v98, v100, v70
	v_mul_f32_e32 v99, v100, v71
	v_mul_f32_e32 v96, v96, v4
	v_mul_f32_e32 v97, v97, v5
	v_mul_f32_e32 v98, v98, v6
	v_mul_f32_e32 v99, v99, v7
	v_cvt_pk_bf16_f32 v68, v96, v97
	v_cvt_pk_bf16_f32 v69, v98, v99
	global_store_dwordx2 v106, v[68:69], s[10:11] offset:512
	v_mul_f32_e32 v96, v100, v72
	v_mul_f32_e32 v97, v100, v73
	v_mul_f32_e32 v98, v100, v74
	v_mul_f32_e32 v99, v100, v75
	v_mul_f32_e32 v96, v96, v8
	v_mul_f32_e32 v97, v97, v9
	v_mul_f32_e32 v98, v98, v10
	v_mul_f32_e32 v99, v99, v11
	v_cvt_pk_bf16_f32 v72, v96, v97
	v_cvt_pk_bf16_f32 v73, v98, v99
	global_store_dwordx2 v106, v[72:73], s[10:11] offset:1024
	v_mul_f32_e32 v96, v100, v76
	v_mul_f32_e32 v97, v100, v77
	v_mul_f32_e32 v98, v100, v78
	v_mul_f32_e32 v99, v100, v79
	v_mul_f32_e32 v96, v96, v12
	v_mul_f32_e32 v97, v97, v13
	v_mul_f32_e32 v98, v98, v14
	v_mul_f32_e32 v99, v99, v15
	v_cvt_pk_bf16_f32 v76, v96, v97
	v_cvt_pk_bf16_f32 v77, v98, v99
; __device__ __forceinline__ unsigned pk2(float lo, float hi) { return pg8::cvt_pk_bf16(lo, hi); }
; #define X_IN INP(0)
; __global__ void __launch_bounds__(512, 2) fwd(Params P) {
;     ...
;         for (int m = gw; m < T_TOK; m += NGW) {
;             const f32x4* xr = (const f32x4*)(X_IN + (size_t)m * DM) + lane; f32x4 v[8]; float s = 0.f;
; #pragma unroll
;             for (int j = 0; j < 8; ++j) { v[j] = __builtin_nontemporal_load(&xr[64 * j]); s += (v[j].x * v[j].x + v[j].y * v[j].y) + (v[j].z * v[j].z + v[j].w * v[j].w); }
;             const float rs = __builtin_amdgcn_rsqf(wave_sum(s) * (1.f / DM) + EPS);
;             u32x2* o = (u32x2*)(XN + (size_t)m * DM) + lane;
; #pragma unroll
;             for (int j = 0; j < 8; ++j) { const f32x4 g = gr[64 * j]; u32x2 w; w.x = pk2(v[j].x * rs * g.x, v[j].y * rs * g.y); w.y = pk2(v[j].z * rs * g.z, v[j].w * rs * g.w); o[64 * j] = w; }
;         }
	global_store_dwordx2 v106, v[76:77], s[10:11] offset:1536
	v_mul_f32_e32 v96, v100, v80
	v_mul_f32_e32 v97, v100, v81
	v_mul_f32_e32 v98, v100, v82
	v_mul_f32_e32 v99, v100, v83
	v_mul_f32_e32 v96, v96, v16
	v_mul_f32_e32 v97, v97, v17
	v_mul_f32_e32 v98, v98, v18
	v_mul_f32_e32 v99, v99, v19
	v_cvt_pk_bf16_f32 v80, v96, v97
	v_cvt_pk_bf16_f32 v81, v98, v99
	global_store_dwordx2 v106, v[80:81], s[10:11] offset:2048
	v_mul_f32_e32 v96, v100, v84
	v_mul_f32_e32 v97, v100, v85
	v_mul_f32_e32 v98, v100, v86
	v_mul_f32_e32 v99, v100, v87
	v_mul_f32_e32 v96, v96, v20
	v_mul_f32_e32 v97, v97, v21
	v_mul_f32_e32 v98, v98, v22
	v_mul_f32_e32 v99, v99, v23
	v_cvt_pk_bf16_f32 v84, v96, v97
	v_cvt_pk_bf16_f32 v85, v98, v99
	global_store_dwordx2 v106, v[84:85], s[10:11] offset:2560
	v_mul_f32_e32 v96, v100, v88
	v_mul_f32_e32 v97, v100, v89
	v_mul_f32_e32 v98, v100, v90
	v_mul_f32_e32 v99, v100, v91
	v_mul_f32_e32 v96, v96, v24
	v_mul_f32_e32 v97, v97, v25
	v_mul_f32_e32 v98, v98, v26
	v_mul_f32_e32 v99, v99, v27
	v_cvt_pk_bf16_f32 v88, v96, v97
	v_cvt_pk_bf16_f32 v89, v98, v99
	global_store_dwordx2 v106, v[88:89], s[10:11] offset:3072
	v_mul_f32_e32 v96, v100, v92
	v_mul_f32_e32 v97, v100, v93
	v_mul_f32_e32 v98, v100, v94
	v_mul_f32_e32 v99, v100, v95
	v_mul_f32_e32 v96, v96, v28
	v_mul_f32_e32 v97, v97, v29
	v_mul_f32_e32 v98, v98, v30
	v_mul_f32_e32 v99, v99, v31
	v_cvt_pk_bf16_f32 v92, v96, v97
	v_cvt_pk_bf16_f32 v93, v98, v99
	global_store_dwordx2 v106, v[92:93], s[10:11] offset:3584
	s_add_i32 s12, s12, s82
	s_cmpk_gt_i32 s12, 0x7fff
	s_cbranch_scc1 .Lp0n_done
	s_lshl_b32 s13, s12, 12
	s_add_u32 s10, s6, s13
	s_addc_u32 s11, s7, 0
	s_add_i32 s13, s12, s82
	s_cmpk_gt_i32 s13, 0x7fff
	s_cselect_b32 s13, s12, s13
	s_lshl_b32 s13, s13, 13
	s_add_u32 s8, s4, s13
	s_addc_u32 s9, s5, 0
	global_load_dwordx4 v[64:67], v166, s[8:9] offset:-4096 nt
	global_load_dwordx4 v[68:71], v166, s[8:9] offset:-3072 nt
	global_load_dwordx4 v[72:75], v166, s[8:9] offset:-2048 nt
	global_load_dwordx4 v[76:79], v166, s[8:9] offset:-1024 nt
	global_load_dwordx4 v[80:83], v166, s[8:9] offset:0 nt
	global_load_dwordx4 v[84:87], v166, s[8:9] offset:1024 nt
	global_load_dwordx4 v[88:91], v166, s[8:9] offset:2048 nt
	global_load_dwordx4 v[92:95], v166, s[8:9] offset:3072 nt
	s_waitcnt vmcnt(23)
	v_mul_f32_e32 v102, v32, v32
	v_mul_f32_e32 v103, v33, v33
	v_mul_f32_e32 v104, v34, v34
	v_mul_f32_e32 v105, v35, v35
	s_waitcnt vmcnt(22)
	v_fma_f32 v102, v36, v36, v102
	v_fma_f32 v103, v37, v37, v103
	v_fma_f32 v104, v38, v38, v104
	v_fma_f32 v105, v39, v39, v105
	s_waitcnt vmcnt(21)
	v_fma_f32 v102, v40, v40, v102
	v_fma_f32 v103, v41, v41, v103
	v_fma_f32 v104, v42, v42, v104
	v_fma_f32 v105, v43, v43, v105
	s_waitcnt vmcnt(20)
	v_fma_f32 v102, v44, v44, v102
	v_fma_f32 v103, v45, v45, v103
	v_fma_f32 v104, v46, v46, v104
	v_fma_f32 v105, v47, v47, v105
	s_waitcnt vmcnt(19)
	v_fma_f32 v102, v48, v48, v102
	v_fma_f32 v103, v49, v49, v103
	v_fma_f32 v104, v50, v50, v104
	v_fma_f32 v105, v51, v51, v105
	s_waitcnt vmcnt(18)
	v_fma_f32 v102, v52, v52, v102
	v_fma_f32 v103, v53, v53, v103
	v_fma_f32 v104, v54, v54, v104
	v_fma_f32 v105, v55, v55, v105
	s_waitcnt vmcnt(17)
	v_fma_f32 v102, v56, v56, v102
	v_fma_f32 v103, v57, v57, v103
	v_fma_f32 v104, v58, v58, v104
	v_fma_f32 v105, v59, v59, v105
	s_waitcnt vmcnt(16)
; __device__ __forceinline__ unsigned pk2(float lo, float hi) { return pg8::cvt_pk_bf16(lo, hi); }
; #define X_IN INP(0)
; __device__ __forceinline__ void xcd_barrier(const XcdBarrier& b) {
;     asm volatile("s_waitcnt vmcnt(0)" ::: "memory");
;     __syncthreads();
;     if (threadIdx.x == 0) {
;         unsigned* bar = b.bar;
;         __builtin_amdgcn_s_waitcnt(0);
;         unsigned nloc = b.st[0], nx = b.st[1];
;         if (nloc == 0u) { xcd_barrier_complete(bar, b.x, nloc, nx); b.st[0] = nloc; b.st[1] = nx; }
; __global__ void __launch_bounds__(512, 2) fwd(Params P) {
;     ...
;             const f32x4* xr = (const f32x4*)(X_IN + (size_t)m * DM) + lane; f32x4 v[8]; float s = 0.f;
; #pragma unroll
;             for (int j = 0; j < 8; ++j) { v[j] = __builtin_nontemporal_load(&xr[64 * j]); s += (v[j].x * v[j].x + v[j].y * v[j].y) + (v[j].z * v[j].z + v[j].w * v[j].w); }
;             const float rs = __builtin_amdgcn_rsqf(wave_sum(s) * (1.f / DM) + EPS);
;             u32x2* o = (u32x2*)(XN + (size_t)m * DM) + lane;
; #pragma unroll
;             for (int j = 0; j < 8; ++j) { const f32x4 g = gr[64 * j]; u32x2 w; w.x = pk2(v[j].x * rs * g.x, v[j].y * rs * g.y); w.y = pk2(v[j].z * rs * g.z, v[j].w * rs * g.w); o[64 * j] = w; }
;         }
	v_fma_f32 v102, v60, v60, v102
	v_fma_f32 v103, v61, v61, v103
	v_fma_f32 v104, v62, v62, v104
	v_fma_f32 v105, v63, v63, v105
	v_add_f32_e32 v102, v102, v103
	v_add_f32_e32 v104, v104, v105
	v_add_f32_e32 v102, v102, v104
	s_nop 1
	v_add_f32_dpp v102, v102, v102 quad_perm:[1,0,3,2] row_mask:0xf bank_mask:0xf
	s_nop 1
	v_add_f32_dpp v102, v102, v102 quad_perm:[2,3,0,1] row_mask:0xf bank_mask:0xf
	s_nop 1
	v_add_f32_dpp v102, v102, v102 row_half_mirror row_mask:0xf bank_mask:0xf
	s_nop 1
	v_add_f32_dpp v102, v102, v102 row_mirror row_mask:0xf bank_mask:0xf
	s_nop 1
	v_readlane_b32 s8, v102, 0
	v_readlane_b32 s9, v102, 16
	v_readlane_b32 vcc_lo, v102, 32
	v_readlane_b32 vcc_hi, v102, 48
	v_mov_b32_e32 v100, s8
	v_add_f32_e32 v100, s9, v100
	v_add_f32_e32 v100, vcc_lo, v100
	v_add_f32_e32 v100, vcc_hi, v100
	v_fmamk_f32 v100, v100, 0x3a000000, v101
	v_rsq_f32_e32 v100, v100
	s_nop 0
	v_mul_f32_e32 v96, v100, v32
	v_mul_f32_e32 v97, v100, v33
	v_mul_f32_e32 v98, v100, v34
	v_mul_f32_e32 v99, v100, v35
	v_mul_f32_e32 v96, v96, v0
	v_mul_f32_e32 v97, v97, v1
	v_mul_f32_e32 v98, v98, v2
	v_mul_f32_e32 v99, v99, v3
	v_cvt_pk_bf16_f32 v32, v96, v97
	v_cvt_pk_bf16_f32 v33, v98, v99
	global_store_dwordx2 v106, v[32:33], s[10:11] offset:0
	v_mul_f32_e32 v96, v100, v36
	v_mul_f32_e32 v97, v100, v37
	v_mul_f32_e32 v98, v100, v38
	v_mul_f32_e32 v99, v100, v39
	v_mul_f32_e32 v96, v96, v4
	v_mul_f32_e32 v97, v97, v5
	v_mul_f32_e32 v98, v98, v6
	v_mul_f32_e32 v99, v99, v7
	v_cvt_pk_bf16_f32 v36, v96, v97
	v_cvt_pk_bf16_f32 v37, v98, v99
	global_store_dwordx2 v106, v[36:37], s[10:11] offset:512
	v_mul_f32_e32 v96, v100, v40
	v_mul_f32_e32 v97, v100, v41
	v_mul_f32_e32 v98, v100, v42
	v_mul_f32_e32 v99, v100, v43
	v_mul_f32_e32 v96, v96, v8
	v_mul_f32_e32 v97, v97, v9
	v_mul_f32_e32 v98, v98, v10
	v_mul_f32_e32 v99, v99, v11
	v_cvt_pk_bf16_f32 v40, v96, v97
	v_cvt_pk_bf16_f32 v41, v98, v99
	global_store_dwordx2 v106, v[40:41], s[10:11] offset:1024
	v_mul_f32_e32 v96, v100, v44
	v_mul_f32_e32 v97, v100, v45
	v_mul_f32_e32 v98, v100, v46
	v_mul_f32_e32 v99, v100, v47
	v_mul_f32_e32 v96, v96, v12
	v_mul_f32_e32 v97, v97, v13
	v_mul_f32_e32 v98, v98, v14
	v_mul_f32_e32 v99, v99, v15
	v_cvt_pk_bf16_f32 v44, v96, v97
	v_cvt_pk_bf16_f32 v45, v98, v99
	global_store_dwordx2 v106, v[44:45], s[10:11] offset:1536
	v_mul_f32_e32 v96, v100, v48
	v_mul_f32_e32 v97, v100, v49
	v_mul_f32_e32 v98, v100, v50
	v_mul_f32_e32 v99, v100, v51
	v_mul_f32_e32 v96, v96, v16
	v_mul_f32_e32 v97, v97, v17
	v_mul_f32_e32 v98, v98, v18
	v_mul_f32_e32 v99, v99, v19
	v_cvt_pk_bf16_f32 v48, v96, v97
	v_cvt_pk_bf16_f32 v49, v98, v99
	global_store_dwordx2 v106, v[48:49], s[10:11] offset:2048
	v_mul_f32_e32 v96, v100, v52
	v_mul_f32_e32 v97, v100, v53
	v_mul_f32_e32 v98, v100, v54
	v_mul_f32_e32 v99, v100, v55
	v_mul_f32_e32 v96, v96, v20
	v_mul_f32_e32 v97, v97, v21
	v_mul_f32_e32 v98, v98, v22
	v_mul_f32_e32 v99, v99, v23
	v_cvt_pk_bf16_f32 v52, v96, v97
	v_cvt_pk_bf16_f32 v53, v98, v99
	global_store_dwordx2 v106, v[52:53], s[10:11] offset:2560
	v_mul_f32_e32 v96, v100, v56
	v_mul_f32_e32 v97, v100, v57
	v_mul_f32_e32 v98, v100, v58
	v_mul_f32_e32 v99, v100, v59
	v_mul_f32_e32 v96, v96, v24
	v_mul_f32_e32 v97, v97, v25
	v_mul_f32_e32 v98, v98, v26
	v_mul_f32_e32 v99, v99, v27
	v_cvt_pk_bf16_f32 v56, v96, v97
	v_cvt_pk_bf16_f32 v57, v98, v99
	global_store_dwordx2 v106, v[56:57], s[10:11] offset:3072
	v_mul_f32_e32 v96, v100, v60
	v_mul_f32_e32 v97, v100, v61
	v_mul_f32_e32 v98, v100, v62
	v_mul_f32_e32 v99, v100, v63
	v_mul_f32_e32 v96, v96, v28
	v_mul_f32_e32 v97, v97, v29
	v_mul_f32_e32 v98, v98, v30
	v_mul_f32_e32 v99, v99, v31
	v_cvt_pk_bf16_f32 v60, v96, v97
	v_cvt_pk_bf16_f32 v61, v98, v99
	global_store_dwordx2 v106, v[60:61], s[10:11] offset:3584
	s_add_i32 s12, s12, s82
	s_cmpk_gt_i32 s12, 0x7fff
	s_cbranch_scc1 .Lp0n_done
	s_branch .Lp0n_loop
.Lp0n_done:
.LBB0_154:
	s_waitcnt vmcnt(0)
	s_barrier
	s_mov_b64 s[4:5], exec
	v_readlane_b32 s6, v246, 0
	v_readlane_b32 s7, v246, 1
	s_and_b64 s[6:7], s[4:5], s[6:7]
	s_mov_b64 exec, s[6:7]
	s_cbranch_execz .LBB0_206
	s_add_i32 s6, 0, 0x20040
	v_mov_b32_e32 v0, s6
	s_waitcnt vmcnt(0) expcnt(0) lgkmcnt(0)
	ds_read_b32 v2, v0
	s_add_i32 s6, 0, 0x20044
	v_mov_b32_e32 v0, s6
	ds_read_b32 v0, v0
	s_waitcnt lgkmcnt(1)
	v_cmp_ne_u32_e32 vcc, 0, v2
	s_cbranch_vccnz .LBB0_170
	v_readlane_b32 s6, v246, 2
	v_readlane_b32 s7, v246, 3
	s_mul_i32 s33, s7, s3
	s_mul_i32 s33, s33, s6
	s_add_u32 s6, s74, 0xc0200
	s_addc_u32 s7, s75, 0
	s_add_u32 s8, s74, 0xc0400
	s_addc_u32 s9, s75, 0
	s_add_u32 s10, s74, 0xc0500
	s_addc_u32 s11, s75, 0
	s_add_u32 s12, s74, 0xc0600
	s_addc_u32 s13, s75, 0
	s_add_u32 s14, s74, 0xc0700
	s_addc_u32 s15, s75, 0
	s_add_u32 s16, s74, 0xc0800
	s_addc_u32 s17, s75, 0
	s_add_u32 s18, s74, 0xc0900
	s_addc_u32 s19, s75, 0
	s_add_u32 s20, s74, 0xc0a00
	s_addc_u32 s21, s75, 0
	s_add_u32 s22, s74, 0xc0b00
	s_addc_u32 s23, s75, 0
	s_add_u32 s24, s74, 0xc0c00
	s_addc_u32 s25, s75, 0
	s_add_u32 s26, s74, 0xc0d00
	s_addc_u32 s27, s75, 0
	s_add_u32 s28, s74, 0xc0e00
	s_addc_u32 s29, s75, 0
	s_add_u32 s30, s74, 0xc0f00
	s_addc_u32 s31, s75, 0
	s_add_u32 s34, s74, 0xc1000
	s_addc_u32 s35, s75, 0
	s_add_u32 s36, s74, 0xc1100
	s_addc_u32 s37, s75, 0
	s_add_u32 s38, s74, 0xc1200
	s_addc_u32 s39, s75, 0
	s_add_u32 s40, s74, 0xc1300
	s_addc_u32 s41, s75, 0
	s_mov_b32 s48, 1
	v_mov_b32_e32 v16, 0
	s_branch .LBB0_158
